# grid barrier: agent-scope invalidate issued at arrival (overlaps with the write-back / polling) instead of after the poll succeeds
# speedup vs baseline: 1.0133x; 1.0133x over previous
; #define LAS __attribute__((address_space(3)))
; __device__ __forceinline__ int otid(int wv) { int ln; asm volatile("v_mbcnt_lo_u32_b32 %0, -1, 0\n\tv_mbcnt_hi_u32_b32 %0, -1, %0" : "=v"(ln)); return wv * 64 + ln; }
; __device__ __forceinline__ unsigned xb_add(unsigned* p, unsigned v) { return __hip_atomic_fetch_add(p, v, __ATOMIC_RELAXED, __HIP_MEMORY_SCOPE_AGENT); }
; __device__ __forceinline__ unsigned xb_xcc_id() { return (unsigned)__builtin_amdgcn_s_getreg((3 << 11) | 20) & 0xFu; }
; __device__ __forceinline__ void grid_bar(int wv, unsigned* bar, volatile LAS unsigned* st) {
;     asm volatile("s_waitcnt vmcnt(0)" ::: "memory");
;     __syncthreads();
;     if (otid(wv) == 0) {
;         __builtin_amdgcn_s_waitcnt(0);
;         const unsigned x = xb_xcc_id();
;         unsigned nloc = st[0], nx = st[1];
;         if (nloc == 0u) { xcd_barrier_complete(bar, x, nloc, nx); st[0] = nloc; st[1] = nx; }
;         const unsigned old = xb_add(&bar[XB_XSUB(x)], 1u);
;         const unsigned gen = old / nloc;
;         if (old + 1u == (gen + 1u) * nloc) {
;             __builtin_amdgcn_fence(__ATOMIC_RELEASE, "agent");
;             asm volatile("s_waitcnt vmcnt(0)" ::: "memory");
;             const unsigned og = xb_add(&bar[XB_TOP], 1u);
;             const unsigned tg = og / nx;
.LBB0_47:
	s_or_b64 exec, exec, s[12:13]
	s_waitcnt vmcnt(0) lgkmcnt(0)
	buffer_inv sc1
	v_readfirstlane_b32 s1, v3
	v_readfirstlane_b32 s2, v2
	s_add_i32 s100, s100, 1
	s_add_i32 s1, s1, 1
	s_mul_i32 s2, s2, s100
	s_add_u32 s10, s6, 0xfabcd00
	s_addc_u32 s11, s7, 0
	v_readfirstlane_b32 s101, v0
	v_mov_b32_e32 v4, 0
	s_cmp_lg_u32 s1, s2
	s_mul_i32 s2, s101, s100
	s_cbranch_scc1 .Lgb_spin_0
	buffer_wbl2 sc1
	v_mov_b32_e32 v5, 1
	s_waitcnt vmcnt(0)
	global_atomic_add v4, v5, s[10:11]

; #define WT_LOAD() do { _Pragma("unroll") for (int i = 0; i < 16; ++i) rg[i] = sp ? sp[(size_t)(k0 + kq + i * 8) * ld] : 0.f; } while (0)
;     __device__ __forceinline__ bool idx(int i, int& Lp) const {
;         const long L = (long)i * G + c; if (L >= n) return false;
;         const int w = (int)L, q = n / 8, r = n % 8, xcd = w % 8, off = w / 8;
;         Lp = (xcd < r ? xcd * (q + 1) : r * (q + 1) + (xcd - r) * q) + off; return true;
;     }
; __device__ __forceinline__ void phase_weights(int wv, const Params& p, int l, LAS unsigned char* lds, int first, int stride) {
;     ...
;     if (ti < 1536) { WT_DECODE(ti); WT_LOAD(); }
.Lgb_done_0:
.LBB0_81:
	s_or_b64 exec, exec, s[4:5]
	s_lshl_b32 s18, s96, 3
	s_lshl_b32 s1, s44, 3
	s_cmpk_lt_i32 s96, 0x600
	v_writelane_b32 v253, s1, 4
	s_cselect_b64 s[2:3], -1, 0
	v_writelane_b32 v253, s2, 5
	s_cmpk_lt_i32 s96, 0x4a0
	s_mov_b32 s57, 0
	v_writelane_b32 v253, s3, 6
	s_cselect_b64 s[2:3], -1, 0
	v_writelane_b32 v253, s2, 7
	s_add_i32 s1, s96, 0xfb60
	s_mul_i32 s36, s44, 24
	v_writelane_b32 v253, s3, 8
	s_and_b32 s2, s1, 0xffff
	s_mul_i32 s2, s2, 0xba2f
	s_lshr_b32 s2, s2, 20
	s_lshl_b32 s3, s2, 6
	s_mul_i32 s2, s2, 22
	s_sub_i32 s1, s1, s2
	s_lshl_b32 s1, s1, 7
	v_writelane_b32 v253, s3, 9
	s_and_b32 s1, s1, 0xff80
	s_lshl_b32 s2, s96, 7
	v_writelane_b32 v253, s1, 10
	s_ashr_i32 s1, s96, 3
	s_and_b32 s2, s2, 0x380
	s_cmp_gt_i32 s1, 15
	v_writelane_b32 v253, s2, 11
	s_cselect_b64 s[2:3], -1, 0
	v_writelane_b32 v253, s2, 12
	s_cmp_gt_u32 s1, 43
	v_mov_b64_e32 v[2:3], 0xa0
	v_writelane_b32 v253, s3, 13
	s_cselect_b64 s[2:3], -1, 0
	s_cmpk_lt_u32 s1, 0x84
	v_writelane_b32 v253, s2, 14
	s_cselect_b64 s[6:7], -1, 0
	s_lshl_b32 s15, s1, 6
	v_writelane_b32 v253, s3, 15
	s_add_i32 s1, s15, 0xfffffc00
	v_writelane_b32 v253, s1, 16
	s_and_b32 s1, s96, 1
	s_add_i32 s1, s1, 1
	s_ashr_i32 s45, s44, 31
	s_ashr_i32 s97, s96, 31
	s_lshl_b32 s5, s96, 9
	s_ashr_i32 s16, s96, 1
	v_writelane_b32 v253, s1, 17
	s_lshl_b64 s[2:3], s[96:97], 9
	s_lshl_b64 s[92:93], s[44:45], 9
	v_writelane_b32 v253, s2, 18
	s_cmp_gt_i32 s96, 47
	v_mov_b32_e32 v197, 0x358637bd
	v_writelane_b32 v253, s3, 19
	s_cselect_b64 s[2:3], -1, 0
	v_writelane_b32 v253, s2, 20
	s_sub_i32 s56, s96, 48
	v_mov_b32_e32 v196, 0xbf1f24be
	v_writelane_b32 v253, s3, 21
	s_lshl_b64 s[2:3], s[56:57], 9
	v_writelane_b32 v253, s2, 22
	s_cmp_lt_i32 s96, 64
	v_mov_b32_e32 v228, 0x3e642e9d
	v_writelane_b32 v253, s3, 23
	s_cselect_b64 s[2:3], -1, 0
	v_writelane_b32 v253, s2, 24
	s_lshr_b32 s1, s97, 29
	v_mov_b32_e32 v232, 0x1000
	v_writelane_b32 v253, s3, 25
	s_add_i32 s2, s96, s1
	s_ashr_i32 s17, s2, 3
	s_and_b32 s2, s2, -8
	s_sub_i32 s14, s96, s2
	s_not_b32 s2, s96
	s_lshl_b32 s3, s14, 3
	s_add_i32 s10, s44, s2
	s_cmp_lt_i32 s10, 16
	s_cselect_b64 s[8:9], -1, 0
	s_ashr_i32 s11, s10, 31
	s_lshr_b32 s4, s11, 29
	v_writelane_b32 v253, s8, 26
	s_add_i32 s4, s10, s4
	s_add_i32 s19, s89, s5
	v_writelane_b32 v253, s9, 27
	s_ashr_i32 s8, s4, 3
	s_and_b32 s4, s4, -8
	v_writelane_b32 v253, s10, 28
	s_sub_i32 s9, s10, s4
	s_lshl_b32 s4, s44, 9
	v_writelane_b32 v253, s11, 29
	s_lshl_b32 s10, s9, 1
	s_add_i32 s12, s44, 0xff
	v_writelane_b32 v253, s5, 30
	s_cmpk_lt_i32 s96, 0x100
	v_writelane_b32 v253, s4, 31
	s_cselect_b64 s[4:5], -1, 0
	s_lshl_b32 s11, s14, 5
	v_writelane_b32 v253, s4, 32
	s_cmpk_gt_i32 s96, 0x5f
	v_mov_b32_e32 v252, 0x2000
	v_writelane_b32 v253, s5, 33
	s_cselect_b64 s[4:5], -1, 0
	s_and_b64 s[4:5], s[4:5], s[22:23]
	v_writelane_b32 v253, s4, 34
	s_cmpk_lt_u32 s96, 0xc0
	s_mov_b32 s23, s57
	v_writelane_b32 v253, s5, 35
	s_cselect_b64 s[4:5], -1, 0
	v_writelane_b32 v253, s4, 36
	s_add_i32 s13, s16, s1
	s_ashr_i32 s1, s13, 3
	v_writelane_b32 v253, s5, 37
	v_writelane_b32 v253, s1, 38
	s_cmp_lt_i32 s14, 0
	s_cselect_b64 s[4:5], -1, 0
	v_writelane_b32 v253, s14, 39
	v_writelane_b32 v253, s4, 40
	s_mul_i32 s1, s14, 9
	s_mul_i32 s14, s14, 33
	v_writelane_b32 v253, s5, 41
	s_and_b64 s[4:5], s[4:5], exec
	s_cselect_b32 s1, s1, s3
	s_cselect_b32 s3, s14, s11
	s_add_i32 s1, s1, s17
	s_bfe_u32 s14, s1, 0x10002
	s_and_b32 s11, s1, 3
	s_ashr_i32 s4, s1, 3
	s_lshl_b32 s1, s14, 23
	s_lshl_b32 s5, s11, 20
	s_or_b32 s1, s1, s5
	s_ashr_i32 s5, s4, 31
	v_writelane_b32 v253, s1, 42
	s_lshl_b64 s[20:21], s[4:5], 22
	v_writelane_b32 v253, s20, 43
	s_lshl_b32 s1, s11, 8
	s_lshl_b64 s[4:5], s[4:5], 21
	v_writelane_b32 v253, s21, 44
	v_writelane_b32 v253, s1, 45
	v_writelane_b32 v253, s4, 46
	s_lshl_b32 s1, s14, 8
	s_mov_b32 s21, s57
	v_writelane_b32 v253, s5, 47
	s_lshl_b32 s4, s11, 18
	v_writelane_b32 v253, s4, 48
	v_writelane_b32 v253, s14, 49
	s_lshl_b32 s4, s14, 9
	v_writelane_b32 v253, s4, 50
	s_and_b32 s4, s13, -8
	s_sub_i32 s4, s16, s4
	v_writelane_b32 v253, s16, 51
	s_cmp_lt_i32 s9, 0
	s_mul_i32 s9, s9, 3
	v_writelane_b32 v253, s4, 52
	s_cselect_b32 s4, s9, s10
	s_add_i32 s5, s4, s8
	s_and_b32 s8, s5, 1
	s_ashr_i32 s4, s5, 1
	s_lshl_b32 s5, s8, 17
	v_writelane_b32 v253, s5, 53
	s_ashr_i32 s5, s4, 31
	s_lshl_b64 s[10:11], s[4:5], 19
	s_lshl_b32 s4, s4, 8
	s_ashr_i32 s5, s4, 31
	s_lshl_b64 s[4:5], s[4:5], 10
	s_lshl_b32 s8, s8, 9
	v_writelane_b32 v253, s10, 54
	s_or_b32 s4, s4, s8
	s_add_u32 s4, s4, 0x1000000
	v_writelane_b32 v253, s11, 55
	v_writelane_b32 v253, s4, 56
	s_addc_u32 s4, s5, 0
	s_add_i32 s3, s3, s17
	v_writelane_b32 v253, s4, 57
	s_ashr_i32 s4, s3, 2
	s_and_b32 s10, s3, 3
	v_writelane_b32 v253, s17, 58
	s_ashr_i32 s5, s4, 31
	s_lshl_b32 s11, s10, 8
	v_writelane_b32 v253, s11, 59
	s_lshl_b64 s[16:17], s[4:5], 19
	s_lshl_b64 s[8:9], s[4:5], 18
	v_writelane_b32 v253, s16, 60
	s_or_b32 s8, s8, s11
	s_lshl_b32 s5, s10, 19
	v_writelane_b32 v253, s17, 61
	s_ashr_i32 s11, s3, 5
	s_lshl_b32 s3, s96, 6
	v_writelane_b32 v253, s5, 62
	s_add_i32 s20, s3, 0xffffe800
	v_writelane_b32 v253, s3, 63
	s_mov_b32 s3, 0xb34c000
	s_and_b64 s[6:7], s[6:7], exec
	s_cselect_b32 s22, s3, 0xbe4c000
	s_cselect_b32 s3, 2, 3
	v_writelane_b32 v254, s3, 0
	s_movk_i32 s3, 0xf500
	s_cselect_b32 s3, s3, 0xffffdf00
	s_abs_i32 s13, s44
	s_waitcnt lgkmcnt(0)
;     __device__ __forceinline__ bool next(int i, Unit& u) const {
;     ...
;         const int r0 = (256 + G - 1) / G;
;         if (i < r0) { g8::ListOrder L{256, G, c}; int q; if (!L.idx(i, q)) return false;
;             const int pm = q >> 2, pn = q & 3; const size_t ro = (size_t)pm * 256 * 1024 + pn * 256;
;             u.a = A + (size_t)pm * a_tile_bytes; u.b = Bt + (size_t)pn * b_tile_bytes;
;             u.p1 = (flags & 1) ? (const float*)((const bf16_t*)base_lat + ro) : (const float*)base_lat + ro;
;             u.o = (flags & 2) ? (char*)((bf16_t*)out_lat + ro) : (char*)((float*)out_lat + ro);
;             u.p2 = gate + (size_t)(pm >> 3) * 6144 + pn * 256; u.nt = ntk; u.mode = 0; u.half = 0; u.mk = -1; u.mneg = 0; return true; }
;         if (!with_ctx) return false;
;         g8::ListOrder L{32 * nsp, G, c}; int q; if (!L.idx(i - r0, q)) return false;
;         const int un = q / nsp, part = q % nsp, pm = un >> 2, pn = un & 3, k0 = part * ntp; const size_t ro = (size_t)pm * 256 * 1024 + pn * 256;
	v_cvt_f32_u32_e32 v0, s13
	s_sub_i32 s5, 0, s13
	s_add_i32 s3, s15, s3
	v_mov_b32_e32 v230, 1
	v_rcp_iflag_f32_e32 v0, v0
	v_mov_b32_e32 v231, 0x1f8
	v_mov_b32_e32 v233, 0x7fc00000
	v_mov_b32_e32 v236, 0x100
	v_mul_f32_e32 v0, 0x4f7ffffe, v0
	v_cvt_u32_f32_e32 v0, v0
	v_mov_b32_e32 v237, 0xbe000000
	v_mov_b32_e32 v238, 0x3e000000
	v_mov_b32_e32 v239, 12
	v_readfirstlane_b32 s6, v0
	s_mul_i32 s5, s5, s6
	s_mul_hi_u32 s5, s6, s5
	s_add_i32 s6, s6, s5
	s_abs_i32 s5, s12
	v_writelane_b32 v254, s6, 1
	s_mul_hi_u32 s6, s5, s6
	s_mul_i32 s7, s6, s13
	v_writelane_b32 v254, s15, 2
	s_sub_i32 s5, s5, s7
	v_writelane_b32 v254, s3, 3
	s_ashr_i32 s3, s12, 31
	s_xor_b32 s3, s3, s45
	s_add_i32 s7, s6, 1
	s_sub_i32 s12, s5, s13
	s_cmp_ge_u32 s5, s13
	s_cselect_b32 s6, s7, s6
	s_cselect_b32 s5, s12, s5
	s_add_i32 s7, s6, 1
	s_cmp_ge_u32 s5, s13
	s_cselect_b32 s5, s7, s6
	s_xor_b32 s5, s5, s3
	s_sub_i32 s3, s5, s3
	s_cmp_lt_i32 s3, 1
	v_writelane_b32 v254, s13, 4
	s_cselect_b64 s[6:7], -1, 0
	v_writelane_b32 v254, s6, 5
	v_mov_b64_e32 v[0:1], 0x80
	v_mov_b32_e32 v240, 2
	v_writelane_b32 v254, s7, 6
	v_writelane_b32 v254, s3, 7
	s_sub_i32 s3, 0, s3
	s_mul_i32 s5, s3, s45
	s_mul_hi_u32 s6, s3, s44
	s_add_i32 s5, s6, s5
	s_mul_i32 s3, s3, s44
	s_add_u32 s6, s3, s96
	s_addc_u32 s7, s5, s97
	s_ashr_i32 s3, s6, 31
	s_lshr_b32 s3, s3, 29
	s_add_i32 s3, s6, s3
	s_ashr_i32 s5, s3, 3
	s_and_b32 s3, s3, -8
	s_sub_i32 s13, s6, s3
	s_lshr_b32 s16, s13, 31
	s_or_b32 s3, s16, 16
	s_mul_i32 s3, s3, s13
	s_add_i32 s3, s3, s5
	s_ashr_i32 s12, s3, 31
	s_lshr_b32 s12, s12, 30
	s_add_i32 s14, s3, s12
	s_and_b32 s12, s14, -4
	s_bfe_u32 s17, s14, 0x20002
	s_ashr_i32 s14, s14, 4
	s_sub_i32 s12, s3, s12
	s_ashr_i32 s15, s14, 31
	s_lshl_b64 s[24:25], s[14:15], 19
	s_lshl_b32 s3, s17, 8
	s_lshl_b32 s14, s12, 2
	s_add_u32 s15, s24, 0x2000000
	v_writelane_b32 v254, s15, 8
	v_writelane_b32 v254, s24, 9
	s_addc_u32 s15, s25, 0
	s_lshl_b64 s[8:9], s[8:9], 1
	v_writelane_b32 v254, s25, 10
	v_writelane_b32 v254, s15, 11
	s_or_b32 s15, s16, 20
	s_mul_i32 s13, s15, s13
	s_add_i32 s5, s13, s5
	s_mul_hi_i32 s13, s5, 0x66666667
	s_lshr_b32 s15, s13, 31
	s_ashr_i32 s13, s13, 1
	s_add_i32 s16, s13, s15
	s_ashr_i32 s15, s14, 31
	s_lshl_b64 s[14:15], s[14:15], 7
	v_writelane_b32 v254, s14, 12
	s_ashr_i32 s13, s12, 31
	s_lshl_b64 s[12:13], s[12:13], 22
	v_writelane_b32 v254, s15, 13
	v_writelane_b32 v254, s12, 14
	v_mov_b32_e32 v241, 0x41b17218
	v_mov_b32_e32 v242, 0x3f80
	v_writelane_b32 v254, s13, 15
	s_lshl_b32 s12, s17, 19
	v_writelane_b32 v254, s12, 16
	s_lshl_b32 s12, s17, 9
	v_writelane_b32 v254, s12, 17
	v_writelane_b32 v254, s8, 18
	s_ashr_i32 s12, s16, 2
	s_ashr_i32 s13, s12, 31
	v_writelane_b32 v254, s9, 19
	s_mul_i32 s8, s16, 5
	s_sub_i32 s8, s5, s8
	s_lshl_b32 s14, s8, 3
	s_ashr_i32 s15, s14, 31
	s_lshl_b64 s[14:15], s[14:15], 7
	v_writelane_b32 v254, s14, 20
	s_and_b32 s17, s16, 3
	s_ashr_i32 s9, s8, 31
	v_writelane_b32 v254, s15, 21
	s_add_i32 s14, s12, 64
	s_lshl_b64 s[12:13], s[12:13], 19
	v_writelane_b32 v254, s12, 22
	s_lshl_b32 s5, s17, 8
	v_mov_b32_e32 v243, 0x3000
	v_writelane_b32 v254, s13, 23
	s_lshl_b32 s12, s17, 9
	v_writelane_b32 v254, s12, 24
	s_lshl_b64 s[12:13], s[8:9], 22
	v_writelane_b32 v254, s12, 25
	s_cmp_eq_u32 s8, 4
	s_mul_hi_i32 s8, s4, 0x160000
	v_writelane_b32 v254, s13, 26
	v_writelane_b32 v254, s8, 27
	s_mul_i32 s4, s4, 0x160000
	v_writelane_b32 v254, s4, 28
	s_cselect_b32 s4, 12, 8
	v_writelane_b32 v254, s4, 29
	s_lshl_b32 s4, s0, 8
	s_ashr_i32 s37, s36, 31
	s_add_i32 s12, s4, 0
	v_writelane_b32 v254, s18, 30
; #define GRID_SYNC() do { const Params pb = ldp(); grid_bar(wv, (unsigned*)(pb.ws + OFF_BAR), (volatile LAS unsigned*)(lds + QWORD_OFF + 4)); } while (0)
; __global__ void __launch_bounds__(512, 2) hybrid_fwd(Params p_unused) {
;     ...
;     for (int l = 0; l < 2; ++l) {
;         const bool need_ctx = (l == 0);
;         const int nM = need_ctx ? 72 : 64;
;         if (PHM & 2) { const Params p = ldp(); phase_norm(wv, p, l, 0, MALL, l == 0 ? 0 : 5, (const float*)(p.ws + OFF_MOD) + (size_t)8 * 6144 + 5120); }
;         { const Params p = ldp(); phase_weights(wv, p, l, lds, c, G); }
;         GRID_SYNC();
;         if (PHM & 8) { const Params p = ldp(); SchedInproj S{{need_ctx ? 792 : 768, G, c}, p.ws, need_ctx ? 0 : 1, (size_t)0 * WSET}; g8::EpiBf E; g8::gemm_phase(wv, lds, 1024, S, E); }
	s_add_i32 s4, s18, 0xffffc000
	v_writelane_b32 v254, s4, 31
	s_lshl_b32 s4, s44, 4
	s_lshl_b64 s[40:41], s[36:37], 11
	s_lshl_b64 s[8:9], s[96:97], 11
	v_writelane_b32 v254, s4, 32
	s_add_u32 s4, s8, 0xea0c000
	v_writelane_b32 v254, s4, 33
	s_addc_u32 s4, s9, 0
	v_writelane_b32 v254, s4, 34
	s_lshl_b32 s4, s44, 10
	s_lshl_b64 s[78:79], s[44:45], 11
	v_writelane_b32 v254, s4, 35
	s_add_u32 s4, s8, 0xfa0c000
	v_writelane_b32 v254, s4, 36
	s_addc_u32 s4, s9, 0
	s_lshl_b64 s[8:9], s[56:57], 11
	v_writelane_b32 v254, s4, 37
	s_add_u32 s4, s8, 0xea0c000
	v_writelane_b32 v254, s4, 38
	s_addc_u32 s4, s9, 0
	v_writelane_b32 v254, s4, 39
	s_lshl_b32 s4, s44, 1
	s_add_i32 s2, s2, s4
	v_writelane_b32 v254, s2, 40
	s_mul_hi_i32 s2, s11, 0x6000
	v_writelane_b32 v254, s2, 41
	s_mul_i32 s2, s11, 0x6000
	v_writelane_b32 v254, s2, 42
	v_writelane_b32 v254, s20, 43
	s_mul_i32 s2, s10, 0x160000
	v_cmp_lt_i64_e64 s[8:9], s[6:7], v[0:1]
	v_writelane_b32 v254, s21, 44
	v_writelane_b32 v254, s2, 45
	v_writelane_b32 v254, s22, 46
	v_cmp_lt_i64_e64 s[6:7], s[6:7], v[2:3]
	s_mul_hi_i32 s2, s14, 0x160000
	v_writelane_b32 v254, s23, 47
	v_writelane_b32 v254, s8, 48
	s_lshl_b32 s0, s0, 7
	s_add_i32 s76, 0, 0x23ff0
	v_writelane_b32 v254, s9, 49
	v_writelane_b32 v254, s6, 50
	s_add_i32 s87, 0, 0x12a00
	v_mov_b32_e32 v1, 0
	v_writelane_b32 v254, s7, 51
	v_writelane_b32 v254, s2, 52
	s_mul_i32 s2, s14, 0x160000
	v_writelane_b32 v254, s2, 53
	s_mul_i32 s2, s17, 0x160000
	v_writelane_b32 v254, s2, 54
	v_writelane_b32 v254, s0, 55
	s_lshl_b32 s0, s1, 1
	v_writelane_b32 v254, s0, 56
	s_lshl_b32 s0, s3, 2
	v_writelane_b32 v254, s0, 57
	s_lshl_b32 s0, s5, 2
	v_writelane_b32 v254, s0, 58
	v_writelane_b32 v254, s19, 59
	s_add_i32 s0, s19, 0xffffa000
	v_writelane_b32 v254, s0, 60
	v_writelane_b32 v254, s12, 61
	s_add_i32 s0, s12, 0x1ec00
	v_writelane_b32 v254, s0, 62
	s_add_i32 s0, 0, 0x23ff4
	v_writelane_b32 v254, s0, 63
	s_add_i32 s0, 0, 0x23ff8
	v_writelane_b32 v255, s0, 0
	s_add_i32 s0, 0, 0x15800
	v_writelane_b32 v255, s0, 1
	s_add_i32 s0, 0, 0x1e400
	v_writelane_b32 v255, s0, 2
	v_writelane_b32 v255, s96, 3
	v_mov_b32_e32 v244, 0x2f40
	v_mov_b32_e32 v245, 4
	v_writelane_b32 v255, s97, 4
	v_writelane_b32 v255, s90, 5
	v_mov_b32_e32 v246, 3
	v_mov_b64_e32 v[202:203], 0xff
	v_writelane_b32 v255, s91, 6
	v_writelane_b32 v255, s89, 7
	v_writelane_b32 v255, s92, 8
	v_mov_b32_e32 v247, 0x7f800000
	s_movk_i32 s69, 0xc0
	v_writelane_b32 v255, s93, 9
	v_writelane_b32 v255, s36, 10
	s_movk_i32 s39, 0x6000
	s_movk_i32 s56, 0x4800
	v_writelane_b32 v255, s37, 11
	v_writelane_b32 v255, s40, 12
	s_mov_b32 s68, 0x800000
	s_movk_i32 s43, 0x4000
	v_writelane_b32 v255, s41, 13
	v_writelane_b32 v255, s78, 14
	s_mov_b32 s83, 0x7f800000
	s_movk_i32 s82, 0x1000
	v_writelane_b32 v255, s79, 15
	v_writelane_b32 v255, s76, 16
	s_movk_i32 s84, 0x2000
	s_movk_i32 s88, 0x3000
	s_movk_i32 s63, 0x5000
	s_movk_i32 s60, 0x7000
	s_mov_b32 s61, 0x8000
	s_mov_b32 s64, 0x9000
	s_mov_b32 s65, 0xa000
	s_mov_b32 s66, 0xb000
	s_mov_b32 s67, 0xc000
	s_mov_b32 s72, 0xd000
	s_mov_b32 s73, 0xe000
	s_mov_b32 s74, 0xf000
	s_mov_b32 s75, 0x10000
	s_movk_i32 s54, 0x7fff
	s_movk_i32 s55, 0x90
	s_mov_b32 s77, 0x2aaaaaab
	s_movk_i32 s86, 0xc40
	s_mov_b32 s33, 0xbfb8aa3b
	s_mov_b32 s2, 0x3f317217
	s_mov_b32 s62, 0x5040100
	s_movk_i32 s85, 0x2400
	s_mov_b32 s71, 0xff800000
	s_add_i32 s70, 0, 0x1a800
	s_mov_b64 s[58:59], 0x80
	s_mov_b64 s[16:17], 0
	s_mov_b64 s[0:1], -1
	s_mov_b32 s94, 0x3a800000
	s_mov_b64 s[80:81], 0x800
	s_mov_b32 s6, s57
	v_writelane_b32 v255, s87, 17
	s_barrier
	s_branch .LBB0_85

; #define LAS __attribute__((address_space(3)))
; __device__ __forceinline__ int otid(int wv) { int ln; asm volatile("v_mbcnt_lo_u32_b32 %0, -1, 0\n\tv_mbcnt_hi_u32_b32 %0, -1, %0" : "=v"(ln)); return wv * 64 + ln; }
; __device__ __forceinline__ unsigned xb_add(unsigned* p, unsigned v) { return __hip_atomic_fetch_add(p, v, __ATOMIC_RELAXED, __HIP_MEMORY_SCOPE_AGENT); }
; __device__ __forceinline__ unsigned xb_xcc_id() { return (unsigned)__builtin_amdgcn_s_getreg((3 << 11) | 20) & 0xFu; }
; __device__ __forceinline__ void grid_bar(int wv, unsigned* bar, volatile LAS unsigned* st) {
;     asm volatile("s_waitcnt vmcnt(0)" ::: "memory");
;     __syncthreads();
;     if (otid(wv) == 0) {
;         __builtin_amdgcn_s_waitcnt(0);
;         const unsigned x = xb_xcc_id();
;         unsigned nloc = st[0], nx = st[1];
;         if (nloc == 0u) { xcd_barrier_complete(bar, x, nloc, nx); st[0] = nloc; st[1] = nx; }
;         const unsigned old = xb_add(&bar[XB_XSUB(x)], 1u);
;         const unsigned gen = old / nloc;
;         if (old + 1u == (gen + 1u) * nloc) {
;             __builtin_amdgcn_fence(__ATOMIC_RELEASE, "agent");
;             asm volatile("s_waitcnt vmcnt(0)" ::: "memory");
;             const unsigned og = xb_add(&bar[XB_TOP], 1u);
;             const unsigned tg = og / nx;
.LBB0_331:
	s_or_b64 exec, exec, s[12:13]
	s_waitcnt vmcnt(0) lgkmcnt(0)
	buffer_inv sc1
	v_readfirstlane_b32 s0, v4
	v_readfirstlane_b32 s1, v3
	s_add_i32 s100, s100, 1
	s_add_i32 s0, s0, 1
	s_mul_i32 s1, s1, s100
	s_add_u32 s4, s8, 0xfabcd00
	s_addc_u32 s5, s9, 0
	v_readfirstlane_b32 s101, v0
	v_mov_b32_e32 v5, 0
	s_cmp_lg_u32 s0, s1
	s_mul_i32 s1, s101, s100
	s_cbranch_scc1 .Lgb_spin_1
	buffer_wbl2 sc1
	v_mov_b32_e32 v6, 1
	s_waitcnt vmcnt(0)
	global_atomic_add v5, v6, s[4:5]

;     __device__ __forceinline__ bool idx(int i, int& Lp, int& half) const {
;         const int R = n / G, T = n % G; long L; half = 0;
;         if (i == R && T > 0 && 2 * T <= G) { if (c >= 2 * T) return false; L = (long)R * G + (c >> 1); half = 1 + (c & 1); }
;         else { L = (long)i * G + c; if (L >= n) return false; }
;         const int w = (int)L, q = n / 8, r = n % 8, xcd = w % 8, off = w / 8;
;         Lp = (xcd < r ? xcd * (q + 1) : r * (q + 1) + (xcd - r) * q) + off; return true;
; __global__ void __launch_bounds__(512, 2) hybrid_fwd(Params p_unused) {
;     ...
;         if (PHM & 8) { const Params p = ldp(); SchedInproj S{{need_ctx ? 792 : 768, G, c}, p.ws, need_ctx ? 0 : 1, (size_t)0 * WSET}; g8::EpiBf E; g8::gemm_phase(wv, lds, 1024, S, E); }
.Lgb_done_1:
.LBB0_365:
	s_or_b64 exec, exec, s[6:7]
	s_mov_b64 s[0:1], s[90:91]
	s_waitcnt lgkmcnt(0)
	s_barrier
	s_load_dwordx2 s[12:13], s[0:1], 0xa8
	v_readlane_b32 s0, v255, 18
	v_readlane_b32 s1, v255, 19
	s_and_b64 s[0:1], s[0:1], exec
	s_movk_i32 s0, 0x318
	s_cselect_b32 s6, s0, 0x300
	v_readlane_b32 s1, v254, 1
	s_mul_hi_u32 s1, s6, s1
	v_readlane_b32 s7, v254, 4
	s_mul_i32 s3, s1, s7
	s_sub_i32 s3, s6, s3
	s_add_i32 s4, s1, 1
	s_sub_i32 s5, s3, s7
	s_cmp_ge_u32 s3, s7
	s_cselect_b32 s1, s4, s1
	s_cselect_b32 s3, s5, s3
	s_add_i32 s4, s1, 1
	s_cmp_ge_u32 s3, s7
	s_cselect_b32 s1, s4, s1
	s_xor_b32 s1, s1, s45
	s_sub_i32 s1, s1, s45
	s_mul_i32 s3, s1, s44
	s_sub_i32 s26, s6, s3
	s_cmp_lg_u32 s1, 0
	v_mbcnt_lo_u32_b32 v0, -1, 0
	v_mbcnt_hi_u32_b32 v0, -1, v0
	s_cselect_b64 s[8:9], -1, 0
	v_add_u32_e32 v2, s89, v0
	s_and_b64 vcc, exec, s[8:9]
	v_readfirstlane_b32 s0, v2
	s_cbranch_vccnz .LBB0_369
	s_lshl_b32 s3, s26, 1
	s_cmp_le_i32 s3, s44
	s_cbranch_scc0 .LBB0_368
	s_cmp_lt_i32 s96, s3
	s_mov_b64 s[8:9], 0
	s_cselect_b64 s[4:5], -1, 0
	s_branch .LBB0_370

; #define LAS __attribute__((address_space(3)))
; __device__ __forceinline__ int otid(int wv) { int ln; asm volatile("v_mbcnt_lo_u32_b32 %0, -1, 0\n\tv_mbcnt_hi_u32_b32 %0, -1, %0" : "=v"(ln)); return wv * 64 + ln; }
; __device__ __forceinline__ unsigned xb_add(unsigned* p, unsigned v) { return __hip_atomic_fetch_add(p, v, __ATOMIC_RELAXED, __HIP_MEMORY_SCOPE_AGENT); }
; __device__ __forceinline__ unsigned xb_xcc_id() { return (unsigned)__builtin_amdgcn_s_getreg((3 << 11) | 20) & 0xFu; }
; __device__ __forceinline__ void grid_bar(int wv, unsigned* bar, volatile LAS unsigned* st) {
;     asm volatile("s_waitcnt vmcnt(0)" ::: "memory");
;     __syncthreads();
;     if (otid(wv) == 0) {
;         __builtin_amdgcn_s_waitcnt(0);
;         const unsigned x = xb_xcc_id();
;         unsigned nloc = st[0], nx = st[1];
;         if (nloc == 0u) { xcd_barrier_complete(bar, x, nloc, nx); st[0] = nloc; st[1] = nx; }
;         const unsigned old = xb_add(&bar[XB_XSUB(x)], 1u);
;         const unsigned gen = old / nloc;
;         if (old + 1u == (gen + 1u) * nloc) {
;             __builtin_amdgcn_fence(__ATOMIC_RELEASE, "agent");
;             asm volatile("s_waitcnt vmcnt(0)" ::: "memory");
;             const unsigned og = xb_add(&bar[XB_TOP], 1u);
;             const unsigned tg = og / nx;
.LBB0_552:
	s_or_b64 exec, exec, s[12:13]
	s_waitcnt vmcnt(0) lgkmcnt(0)
	buffer_inv sc1
	v_readfirstlane_b32 s0, v4
	v_readfirstlane_b32 s1, v3
	s_add_i32 s100, s100, 1
	s_add_i32 s0, s0, 1
	s_mul_i32 s1, s1, s100
	s_add_u32 s4, s8, 0xfabcd00
	s_addc_u32 s5, s9, 0
	v_readfirstlane_b32 s101, v2
	v_mov_b32_e32 v5, 0
	s_cmp_lg_u32 s0, s1
	s_mul_i32 s1, s101, s100
	s_cbranch_scc1 .Lgb_spin_2
	buffer_wbl2 sc1
	v_mov_b32_e32 v6, 1
	s_waitcnt vmcnt(0)
	global_atomic_add v5, v6, s[4:5]

; __device__ __forceinline__ unsigned xb_ld(unsigned* p)              { return __hip_atomic_load(p, __ATOMIC_RELAXED, __HIP_MEMORY_SCOPE_AGENT); }
; #define XB_SPIN(cond, bar) do { unsigned _sp = 0; while (cond) { __builtin_amdgcn_s_sleep(1); \
;     if ((++_sp & 255u) == 0u) { if (xb_ld(&(bar)[XB_TMO])) break; if (_sp > XB_SPIN_CAP) { atomicAdd(&(bar)[XB_TMO], 1u); break; } } } } while (0)
; __device__ __forceinline__ void grid_bar(int wv, unsigned* bar, volatile LAS unsigned* st) {
;     ...
;             XB_SPIN(xb_ld(&bar[XB_XGEN(x)]) == gen, bar);
;             __builtin_amdgcn_fence(__ATOMIC_ACQUIRE, "agent");
;             asm volatile("s_waitcnt vmcnt(0)" ::: "memory");
;         }
;     }
;     __syncthreads();
; }
.Lgb_done_2:
	s_branch .Lgb_end_2

; __device__ __forceinline__ int otid(int wv) { int ln; asm volatile("v_mbcnt_lo_u32_b32 %0, -1, 0\n\tv_mbcnt_hi_u32_b32 %0, -1, %0" : "=v"(ln)); return wv * 64 + ln; }
; __device__ __forceinline__ void gla_scan(int wv, const Params& p) {
;     bf16_t* S = (bf16_t*)(p.ws + OFF_S); const float* DEC = (const float*)(p.ws + OFF_DEC);
;     for (int e = blockIdx.x * 512 + otid(wv); e < 147456; e += gridDim.x * 512) {
;         const int chain = e / 2304, idx = (e % 2304) * 2, dk = idx % 48, dir = chain & 1; const size_t base = (size_t)chain * 36;
;         float s0 = 0.f, s1 = 0.f;
;         for (int st0 = 0; st0 < 36; st0 += 6) { unsigned v[6]; float d0[6], d1[6]; unsigned* sp[6];
; #pragma unroll
;             for (int u = 0; u < 6; ++u) { const int st = st0 + u, n = dir ? 35 - st : (st < 4 ? 32 + st : st - 4); sp[u] = (unsigned*)(S + (base + n) * 4608 + idx); v[u] = *sp[u];
;                 const float* dp = DEC + (base + n) * 48 + dk; d0[u] = dp[0]; d1[u] = dp[1]; }
.Lgb_done_3:
.LBB0_882:
	s_or_b64 exec, exec, s[6:7]
	s_mov_b64 s[4:5], s[90:91]
	s_waitcnt lgkmcnt(0)
	s_barrier
	v_mbcnt_lo_u32_b32 v0, -1, 0
	v_mbcnt_hi_u32_b32 v0, -1, v0
	v_readlane_b32 s0, v254, 59
	s_nop 1
	v_add_u32_e32 v0, s0, v0
	s_mov_b32 s0, 0x24000
	v_cmp_gt_i32_e32 vcc, s0, v0
	s_and_saveexec_b64 s[6:7], vcc
	s_cbranch_execz .LBB0_887
	s_load_dwordx2 s[0:1], s[4:5], 0xa8
	s_mov_b64 s[12:13], 0
	s_waitcnt lgkmcnt(0)
	s_add_u32 s8, s0, 0x9920000
	s_addc_u32 s9, s1, 0
	s_add_u32 s10, s0, 0xad60000
	s_addc_u32 s11, s1, 0

; __device__ __forceinline__ int otid(int wv) { int ln; asm volatile("v_mbcnt_lo_u32_b32 %0, -1, 0\n\tv_mbcnt_hi_u32_b32 %0, -1, %0" : "=v"(ln)); return wv * 64 + ln; }
; #define G8_STAGE(bufoff, gbase, voff) do { _Pragma("unroll") for (int _i = 0; _i < 2; ++_i) \
;         __builtin_amdgcn_global_load_lds((const unsigned*)((const char*)(gbase) + (voff)[_i]), (LAS unsigned*)(lds + (bufoff) + ldsw + _i * 8192), 16, 0, 0); } while (0)
; #define G8_WAIT_V(n) asm volatile("s_waitcnt vmcnt(" #n ")" ::: "memory")
; #define G8_BAR __builtin_amdgcn_s_barrier()
; template <class Epi, class Sched>
; __device__ __forceinline__ void gemm_phase(int wv, LAS unsigned char* lds, const int K, const Sched& S, const Epi& E) {
;     const int tid = otid(wv), wid = __builtin_amdgcn_readfirstlane(tid >> 6), lane = tid & 63, wr = wid >> 2, wc = wid & 3, fr = lane & 15, fq = lane >> 4;
;     unsigned voffA[2], voffB[2];
; #pragma unroll
;     for (int i = 0; i < 2; ++i) { int R, C; stage_rc(tid * 16 + i * 8192, R, C); const int Rb = Epi::PERM ? ((R & ~31) + perm32(R & 31)) : R;
;         voffA[i] = (unsigned)(R * K + C) * 2u; voffB[i] = (unsigned)(Rb * K + C) * 2u; }
;     const size_t kstep = (size_t)(BK * 2);
;     const size_t hstep = (size_t)HALF * K * 2;
;     const unsigned ldsw = (unsigned)wid * 1024u;
;     const int aoff = lds_byte(wr * 64 + fr, fq * 8), boff = lds_byte(wc * 32 + fr, fq * 8);
;     ...
;     Unit cur, nxt; int ui = 0;
;     if (!S.next(0, cur)) return;
;     f32x4 acc[2][2][4][2];
; #pragma unroll
;     for (int a = 0; a < 2; ++a)
; #pragma unroll
;         for (int b = 0; b < 2; ++b)
; #pragma unroll
;             for (int m = 0; m < 4; ++m)
; #pragma unroll
;                 for (int n = 0; n < 2; ++n) acc[a][b][m][n] = (f32x4){0.f, 0.f, 0.f, 0.f};
;     bf16x8 At[4][2], B0[2][2], B1[2][2];
;     const char* cA = cur.a; const char* cB = cur.b;
;     G8_STAGE(G8_SB(0, 0), cB, voffB); G8_STAGE(G8_SA(0, 0), cA, voffA); G8_STAGE(G8_SB(0, 1), cB + hstep, voffB); G8_STAGE(G8_SA(0, 1), cA + hstep, voffA);
;     if (wr == 1) G8_BAR;
;     G8_WAIT_V(4); G8_BAR;
;     G8_STAGE(G8_SB(1, 0), cB + kstep, voffB); G8_STAGE(G8_SA(1, 0), cA + kstep, voffA); G8_STAGE(G8_SB(1, 1), cB + hstep + kstep, voffB);
;     G8_WAIT_V(6); G8_BAR;
.Lgb_done_4:
.LBB0_939:
	s_or_b64 exec, exec, s[6:7]
	v_readlane_b32 s0, v255, 18
	v_readlane_b32 s1, v255, 19
	s_and_b64 s[0:1], s[0:1], exec
	s_mov_b64 s[4:5], s[90:91]
	s_cselect_b32 s28, 0x48, 64
	s_waitcnt lgkmcnt(0)
	s_barrier
	v_mbcnt_lo_u32_b32 v11, -1, 0
	v_mbcnt_hi_u32_b32 v11, -1, v11
	s_cmp_ge_i32 s96, s28
	v_add_u32_e32 v2, s89, v11
	s_nop 0
	v_readfirstlane_b32 s0, v2
	s_cbranch_scc1 .LBB0_951
	v_lshlrev_b32_e32 v3, 4, v2
	v_add_u32_e32 v4, 0x2000, v3
	v_ashrrev_i32_e32 v0, 31, v4
	v_lshrrev_b32_e32 v0, 22, v0
	v_add_u32_e32 v0, v4, v0
	v_ashrrev_i32_e32 v0, 10, v0
	v_mul_i32_i24_e32 v5, 0x400, v0
	v_sub_u32_e32 v4, v4, v5
	v_lshrrev_b32_e32 v5, 4, v4
	v_bitop3_b32 v4, v5, v4, 32 bitop3:0x6c
	v_ashrrev_i32_e32 v5, 31, v4
	v_lshrrev_b32_e32 v5, 26, v5
	v_add_u32_e32 v5, v4, v5
	v_lshlrev_b32_e32 v7, 3, v0
	v_ashrrev_i32_e32 v6, 6, v5
	v_and_b32_e32 v7, -16, v7
	v_add_u32_e32 v8, v6, v7
	v_and_b32_e32 v7, 3, v6
	s_mov_b32 s3, 0x3fffe0
	v_lshrrev_b32_e32 v9, 2, v8
	v_lshlrev_b32_e32 v10, 1, v8
	v_and_b32_e32 v5, 0xc0, v5
	v_and_or_b32 v7, v8, s3, v7
	v_and_b32_e32 v9, 4, v9
	v_and_b32_e32 v10, 24, v10
	v_sub_u32_e32 v4, v4, v5
	v_or3_b32 v9, v7, v9, v10
	v_lshlrev_b32_e32 v7, 5, v0
	v_ashrrev_i16_sdwa v4, v230, sext(v4) dst_sel:DWORD dst_unused:UNUSED_PAD src0_sel:DWORD src1_sel:BYTE_0
	v_and_b32_e32 v10, 32, v7
	v_bfe_i32 v7, v4, 0, 16
	v_add_lshl_u32 v4, v10, v7, 1
	v_lshl_add_u32 v132, v9, 10, v4
	v_lshl_add_u32 v134, v8, 10, v4
	v_bfe_i32 v4, v2, 27, 1
	v_lshrrev_b32_e32 v4, 22, v4
	v_add_u32_e32 v4, v3, v4
	v_and_b32_e32 v4, 0xfffffc00, v4
	v_sub_u32_e32 v3, v3, v4
	v_lshrrev_b32_e32 v4, 4, v3
	v_ashrrev_i32_e32 v5, 31, v2
	v_bitop3_b32 v3, v4, v3, 32 bitop3:0x6c
	v_lshrrev_b32_e32 v5, 26, v5
	v_ashrrev_i32_e32 v4, 31, v3
	v_add_u32_e32 v2, v2, v5
	v_lshrrev_b32_e32 v4, 26, v4
	v_ashrrev_i32_e32 v9, 6, v2
	v_add_u32_e32 v4, v3, v4
	v_lshlrev_b32_e32 v2, 3, v9
	v_ashrrev_i32_e32 v8, 6, v4
	v_and_b32_e32 v2, -16, v2
	v_add_u32_e32 v2, v8, v2
	v_and_b32_e32 v5, 3, v8
	s_load_dwordx2 s[8:9], s[4:5], 0xa8
	s_ashr_i32 s4, s0, 6
	v_and_or_b32 v5, v2, s3, v5
	s_lshr_b32 s3, s28, 3
	v_readlane_b32 s6, v253, 40
	s_ashr_i32 s5, s0, 8
	s_lshl_b32 s1, s4, 10
	s_add_i32 s24, s3, 1
	v_readlane_b32 s7, v253, 41
	s_and_b64 s[6:7], s[6:7], exec
	s_cselect_b32 s6, s24, s3
	v_readlane_b32 s7, v253, 39
	s_mul_i32 s6, s6, s7
	v_readlane_b32 s7, v253, 58
	s_add_i32 s10, s6, s7
	s_waitcnt lgkmcnt(0)
	s_add_u32 s25, s8, 0x8720000
	s_addc_u32 s26, s9, 0
	s_ashr_i32 s11, s10, 31
	v_lshrrev_b32_e32 v10, 2, v2
	s_waitcnt vmcnt(8)
	v_lshlrev_b32_e32 v12, 1, v2
	v_and_b32_e32 v4, 0xc0, v4
	s_lshl_b64 s[6:7], s[10:11], 18
	v_and_b32_e32 v10, 4, v10
	v_and_b32_e32 v12, 24, v12
	v_sub_u32_e32 v3, v3, v4
	s_add_u32 s16, s25, s6
	v_or3_b32 v5, v5, v10, v12
	v_lshlrev_b32_e32 v10, 5, v9
	v_ashrrev_i16_sdwa v3, v230, sext(v3) dst_sel:DWORD dst_unused:UNUSED_PAD src0_sel:DWORD src1_sel:BYTE_0
	s_addc_u32 s17, s26, s7
	v_and_b32_e32 v12, 32, v10
	v_bfe_i32 v10, v3, 0, 16
	s_add_u32 s6, s8, 0xc5cc000
	v_add_lshl_u32 v3, v12, v10, 1
	s_addc_u32 s7, s9, 0
	s_add_i32 s27, s1, 0
	v_lshl_add_u32 v136, v5, 10, v3
	s_add_i32 m0, s27, 0x10000
	v_lshl_add_u32 v138, v2, 10, v3
	global_load_lds_dwordx4 v136, s[6:7]
	s_add_i32 m0, s27, 0x12000
	s_add_i32 s30, s27, 0x2000
	global_load_lds_dwordx4 v132, s[6:7]
	s_mov_b32 m0, s27
	s_add_u32 s12, s8, 0xc5ec000
	global_load_lds_dwordx4 v138, s[16:17]
	s_mov_b32 m0, s30
	s_addc_u32 s13, s9, 0
	global_load_lds_dwordx4 v134, s[16:17]
	s_add_i32 m0, s27, 0x14000
	v_mov_b32_e32 v139, v1
	global_load_lds_dwordx4 v136, s[12:13]
	s_add_i32 m0, s27, 0x16000
	v_mov_b32_e32 v135, v1
	global_load_lds_dwordx4 v132, s[12:13]
	s_add_u32 s12, s16, 0x20000
	s_addc_u32 s13, s17, 0
	s_add_i32 s31, s27, 0x4000
	s_mov_b32 m0, s31
	s_add_i32 s34, s27, 0x6000
	global_load_lds_dwordx4 v138, s[12:13]
	s_mov_b32 m0, s34
	v_lshl_add_u64 v[4:5], s[16:17], 0, v[138:139]
	global_load_lds_dwordx4 v134, s[12:13]
	s_cmp_lg_u32 s5, 1
	v_lshl_add_u64 v[2:3], s[16:17], 0, v[134:135]
	s_cbranch_scc1 .LBB0_942
	s_barrier

;     __device__ __forceinline__ bool next(int i, Unit& u) const {
;         u.ldo = 1024; u.cmax = flags;
;         const int r0 = (256 + G - 1) / G;
;         if (i < r0) { g8::ListOrder L{256, G, c}; int q; if (!L.idx(i, q)) return false;
;             const int pm = q >> 2, pn = q & 3; const size_t ro = (size_t)pm * 256 * 1024 + pn * 256;
;             u.a = A + (size_t)pm * a_tile_bytes; u.b = Bt + (size_t)pn * b_tile_bytes;
;             u.p1 = (flags & 1) ? (const float*)((const bf16_t*)base_lat + ro) : (const float*)base_lat + ro;
;             u.o = (flags & 2) ? (char*)((bf16_t*)out_lat + ro) : (char*)((float*)out_lat + ro);
;             u.p2 = gate + (size_t)(pm >> 3) * 6144 + pn * 256; u.nt = ntk; u.mode = 0; u.half = 0; u.mk = -1; u.mneg = 0; return true; }
;         if (!with_ctx) return false;
;         g8::ListOrder L{32 * nsp, G, c}; int q; if (!L.idx(i - r0, q)) return false;
;         const int un = q / nsp, part = q % nsp, pm = un >> 2, pn = un & 3, k0 = part * ntp; const size_t ro = (size_t)pm * 256 * 1024 + pn * 256;
;         u.a = A + (size_t)(64 + pm) * a_tile_bytes + (size_t)k0 * 128; u.b = Bt + (size_t)pn * b_tile_bytes + (size_t)k0 * 128;
;         u.p1 = nullptr; u.o = (char*)(ws + OFF_S) + ((size_t)part * 2048 * 1024 + ro) * 2; u.p2 = gate + (size_t)8 * 6144 + pn * 256;
;         u.nt = (part == nsp - 1) ? (ntk - k0) : ntp; u.mode = 1; u.half = 0; u.mk = -1; u.mneg = 0; return true;
; __global__ void __launch_bounds__(512, 2) hybrid_fwd(Params p_unused) {
;     ...
;         if (PHM & 1024) { const Params p = ldp(); const float* mod = (const float*)(p.ws + OFF_MOD); SchedRes S{G, c, need_ctx ? 1 : 0, 4, 16, 4, p.ws, (const char*)(p.ws + OFF_HY), (size_t)256 * 2048, (const char*)(p.ws + OFF_WOUT + (size_t)0 * WSET), (size_t)256 * 2048,
;                      l == 0 ? (const void*)p.x : (const void*)(p.ws + OFF_XB), (void*)(p.ws + OFF_XB), l == 0 ? 2 : 3, mod + (size_t)l * 9 * 6144 + 2048};
;           g8::EpiRes E; g8::gemm_phase(wv, lds, 1024, S, E); }
.Lgb_done_5:
.LBB0_1066:
	s_or_b64 exec, exec, s[6:7]
	s_mov_b64 s[0:1], s[90:91]
	s_waitcnt lgkmcnt(0)
	s_barrier
	s_load_dwordx2 s[4:5], s[0:1], 0x0
	s_load_dwordx2 s[8:9], s[0:1], 0xa8
	v_mbcnt_lo_u32_b32 v0, -1, 0
	v_mbcnt_hi_u32_b32 v0, -1, v0
	s_mov_b64 s[12:13], -1
	v_add_u32_e32 v2, s89, v0
	s_waitcnt lgkmcnt(0)
	s_add_u32 s0, s8, 0x800000
	s_addc_u32 s1, s9, 0
	s_add_u32 s29, s8, 0xbe4c000
	s_addc_u32 s46, s9, 0
	s_add_u32 s47, s8, 0xc60c000
	s_addc_u32 s56, s9, 0
	s_and_b64 s[6:7], s[86:87], exec
	v_readlane_b32 s6, v255, 24
	v_readlane_b32 s7, v255, 25
	s_cselect_b32 s66, s5, s56
	s_cselect_b32 s67, s4, s47
	s_cselect_b32 s4, 2, 3
	s_lshl_b64 s[20:21], s[6:7], 2
	s_add_u32 s5, s8, s20
	s_addc_u32 s22, s9, s21
	v_readlane_b32 s6, v254, 5
	s_add_u32 s72, s5, 0xfa4e000
	v_readlane_b32 s7, v254, 6
	s_addc_u32 s73, s22, 0
	s_and_b64 vcc, exec, s[6:7]
	v_readlane_b32 s6, v255, 26
	v_readlane_b32 s7, v255, 27
	v_readfirstlane_b32 s74, v2
	s_nop 0
	v_cndmask_b32_e64 v3, 0, 1, s[6:7]
	v_cmp_ne_u32_e64 s[10:11], 1, v3
	s_cbranch_vccz .LBB0_1070
	s_mov_b64 s[12:13], 0
	s_and_b64 vcc, exec, s[10:11]
	s_mov_b64 s[18:19], 0
	s_cbranch_vccnz .LBB0_1070
	v_readlane_b32 s6, v254, 48
	v_readlane_b32 s7, v254, 49
	s_andn2_b64 vcc, exec, s[6:7]
	s_cbranch_vccnz .LBB0_1070
	v_readlane_b32 s3, v254, 8
	s_add_u32 s3, s0, s3
	v_readlane_b32 s6, v254, 11
	s_addc_u32 s6, s1, s6
	v_readlane_b32 s14, v254, 12
	v_readlane_b32 s15, v254, 13
	s_add_u32 s38, s3, s14
	s_addc_u32 s39, s6, s15
	v_readlane_b32 s3, v254, 16
	s_add_u32 s3, s29, s3
	s_addc_u32 s6, s46, 0
	s_add_u32 s40, s3, s14
	s_addc_u32 s41, s6, s15
	v_readlane_b32 s6, v254, 14
	v_readlane_b32 s7, v254, 15
	s_add_u32 s3, s8, s6
	s_addc_u32 s6, s9, s7
	v_readlane_b32 s14, v254, 9
	v_readlane_b32 s15, v254, 10
	s_add_u32 s3, s3, s14
	s_addc_u32 s6, s6, s15
	v_readlane_b32 s7, v254, 17
	s_add_u32 s3, s3, s7
	s_addc_u32 s6, s6, 0
	s_add_u32 s16, s3, 0x9920000
	s_addc_u32 s17, s6, 0
	v_readlane_b32 s3, v254, 57
	s_add_u32 s3, s5, s3
	s_addc_u32 s6, s22, 0
	s_add_u32 s14, s3, 0xfa7e000
	s_addc_u32 s15, s6, 0
	s_mov_b64 s[6:7], 0
	s_mov_b32 s96, 4
	s_mov_b32 s95, 1
	s_mov_b64 s[18:19], -1

; #define LAS __attribute__((address_space(3)))
; __device__ __forceinline__ int otid(int wv) { int ln; asm volatile("v_mbcnt_lo_u32_b32 %0, -1, 0\n\tv_mbcnt_hi_u32_b32 %0, -1, %0" : "=v"(ln)); return wv * 64 + ln; }
; __device__ __forceinline__ unsigned xb_add(unsigned* p, unsigned v) { return __hip_atomic_fetch_add(p, v, __ATOMIC_RELAXED, __HIP_MEMORY_SCOPE_AGENT); }
; __device__ __forceinline__ unsigned xb_xcc_id() { return (unsigned)__builtin_amdgcn_s_getreg((3 << 11) | 20) & 0xFu; }
; __device__ __forceinline__ void grid_bar(int wv, unsigned* bar, volatile LAS unsigned* st) {
;     asm volatile("s_waitcnt vmcnt(0)" ::: "memory");
;     __syncthreads();
;     if (otid(wv) == 0) {
;         __builtin_amdgcn_s_waitcnt(0);
;         const unsigned x = xb_xcc_id();
;         unsigned nloc = st[0], nx = st[1];
;         if (nloc == 0u) { xcd_barrier_complete(bar, x, nloc, nx); st[0] = nloc; st[1] = nx; }
;         const unsigned old = xb_add(&bar[XB_XSUB(x)], 1u);
;         const unsigned gen = old / nloc;
;         if (old + 1u == (gen + 1u) * nloc) {
;             __builtin_amdgcn_fence(__ATOMIC_RELEASE, "agent");
;             asm volatile("s_waitcnt vmcnt(0)" ::: "memory");
;             const unsigned og = xb_add(&bar[XB_TOP], 1u);
;             const unsigned tg = og / nx;
.LBB0_1181:
	s_or_b64 exec, exec, s[16:17]
	s_waitcnt vmcnt(0) lgkmcnt(0)
	buffer_inv sc1
	v_readfirstlane_b32 s0, v4
	v_readfirstlane_b32 s1, v3
	s_add_i32 s100, s100, 1
	s_add_i32 s0, s0, 1
	s_mul_i32 s1, s1, s100
	s_add_u32 s4, s8, 0xfabcd00
	s_addc_u32 s5, s9, 0
	v_readfirstlane_b32 s101, v2
	v_mov_b32_e32 v5, 0
	s_cmp_lg_u32 s0, s1
	s_mul_i32 s1, s101, s100
	s_cbranch_scc1 .Lgb_spin_6
	buffer_wbl2 sc1
	v_mov_b32_e32 v6, 1
	s_waitcnt vmcnt(0)
	global_atomic_add v5, v6, s[4:5]

; __device__ __forceinline__ float bflo(unsigned w) { return __uint_as_float(w << 16); }
; __device__ __forceinline__ float bfhi(unsigned w) { return __uint_as_float(w & 0xffff0000u); }
; __device__ __forceinline__ int otid(int wv) { int ln; asm volatile("v_mbcnt_lo_u32_b32 %0, -1, 0\n\tv_mbcnt_hi_u32_b32 %0, -1, %0" : "=v"(ln)); return wv * 64 + ln; }
; __device__ __forceinline__ void phase_norm(int wv, const Params& p, int l, int which, int nrows, int nparts, const float* rgate) {
;     const int tid = otid(wv), lane = tid & 63, gw = blockIdx.x * 8 + (tid >> 6), nw = gridDim.x * 8;
;     const float* mod = (const float*)(p.ws + OFF_MOD) + (size_t)l * 9 * 6144;
;     const float* gain = (which ? p.norm_ffn : p.norm_mix) + l * 1024;
;     bf16_t* H = (bf16_t*)(p.ws + OFF_HY);
;     const bf16_t* XB = (const bf16_t*)(p.ws + OFF_XB);
;     const bool wide = !(l == 0 && which == 0);
;     int cq[4];
; #pragma unroll
;     for (int q = 0; q < 4; ++q) cq[q] = wide ? (q >> 1) * 512 + lane * 8 + (q & 1) * 4 : q * 256 + lane * 4;
;     for (int row0 = gw; row0 < nrows; row0 += 3 * nw) {
;         f32x4 v[3][4]; float ss[3];
; #pragma unroll
;         for (int u = 0; u < 3; ++u) { const int row = row0 + u * nw; ss[u] = 0.f;
;             if (row < nrows) { const bool lat = row < MLAT;
;                 if (!wide) { const float* src = lat ? p.x + (size_t)row * 1024 : p.ctx + (size_t)(row - MLAT) * 1024;
; #pragma unroll
;                     for (int q = 0; q < 4; ++q) v[u][q] = *(const f32x4*)(src + cq[q]); }
;                 else {
; #pragma unroll
;                     for (int jj = 0; jj < 2; ++jj) { const u32x4 w = *(const u32x4*)(XB + (size_t)row * 1024 + jj * 512 + lane * 8);
;                         v[u][2 * jj] = (f32x4){bflo(w.x), bfhi(w.x), bflo(w.y), bfhi(w.y)}; v[u][2 * jj + 1] = (f32x4){bflo(w.z), bfhi(w.z), bflo(w.w), bfhi(w.w)}; } } }
.Lgb_done_6:
.LBB0_1215:
	s_or_b64 exec, exec, s[6:7]
	s_mov_b64 s[4:5], s[90:91]
	s_waitcnt lgkmcnt(0)
	s_barrier
	v_mbcnt_lo_u32_b32 v0, -1, 0
	v_mbcnt_hi_u32_b32 v0, -1, v0
	v_readlane_b32 s1, v254, 30
	v_add_u32_e32 v2, s89, v0
	v_ashrrev_i32_e32 v3, 6, v2
	s_lshl_b32 s0, s28, 8
	v_add_u32_e32 v2, s1, v3
	v_cmp_gt_i32_e32 vcc, s0, v2
	s_and_saveexec_b64 s[18:19], vcc
	s_cbranch_execz .LBB0_1236
	s_load_dwordx2 s[22:23], s[4:5], 0xa8
	s_nop 0
	s_load_dwordx2 s[4:5], s[4:5], 0x38
	v_readlane_b32 s8, v255, 22
	v_readlane_b32 s9, v255, 23
	v_and_b32_e32 v5, 63, v0
	s_waitcnt lgkmcnt(0)
	s_add_u32 s1, s22, s20
	s_addc_u32 s3, s23, s21
	s_add_u32 s24, s1, 0xfa4c000
	s_addc_u32 s25, s3, 0
	s_add_u32 s6, s1, 0xfa7e000
	s_addc_u32 s7, s3, 0
	s_lshl_b32 s56, s8, 10
	s_lshl_b64 s[8:9], s[56:57], 2
	s_add_u32 s4, s4, s8
	v_readlane_b32 s3, v254, 31
	s_addc_u32 s5, s5, s9
	v_lshlrev_b32_e32 v44, 3, v5
	v_add_u32_e32 v58, s3, v3
	v_ashrrev_i32_e32 v3, 31, v2
	v_or_b32_e32 v6, 0x200, v44
	s_add_u32 s8, s22, 0xc60c000
	v_lshlrev_b32_e32 v0, 4, v5
	v_lshlrev_b32_e32 v12, 5, v5
	v_mov_b32_e32 v13, v1
	v_lshlrev_b64 v[2:3], 11, v[2:3]
	v_lshlrev_b32_e32 v7, 2, v5
	v_or_b32_e32 v4, 0x204, v44
	v_or_b32_e32 v8, 4, v44
	s_addc_u32 s9, s23, 0
	v_lshl_add_u64 v[10:11], s[22:23], 0, v[0:1]
	s_mov_b64 s[14:15], 0x800000
	v_lshlrev_b32_e32 v14, 2, v6
	v_mov_b32_e32 v15, v1
	v_lshl_add_u64 v[54:55], s[4:5], 0, v[12:13]
	s_mov_b64 s[4:5], 0x9920000
	v_or_b32_e32 v2, v2, v0
	s_mov_b32 s43, 0xa520000
	s_mov_b32 s37, 0xa120000
	s_mov_b32 s36, 0x9d20000
	s_mov_b32 s35, 0x9920000
	s_mov_b32 s34, 0xc00000
	s_mov_b32 s31, 0x400000
	s_movk_i32 s30, 0x3fff
	v_readlane_b32 s29, v254, 32
	v_readlane_b32 s1, v253, 4
	v_lshl_add_u64 v[46:47], s[8:9], 0, v[0:1]
	v_lshl_add_u64 v[48:49], v[10:11], 0, s[14:15]
	v_lshl_add_u64 v[50:51], s[6:7], 0, v[12:13]
	v_lshl_add_u64 v[52:53], s[6:7], 0, v[14:15]
	v_xor_b32_e32 v45, 0x80, v7
	v_xor_b32_e32 v90, 64, v7
	v_xor_b32_e32 v91, 32, v7
	v_xor_b32_e32 v92, 16, v7
	v_xor_b32_e32 v93, 8, v7
	v_xor_b32_e32 v94, 4, v7
	v_lshl_add_u64 v[56:57], v[10:11], 0, s[4:5]
	v_lshl_add_u64 v[60:61], s[8:9], 0, v[2:3]
	s_mov_b64 s[26:27], 0
	v_lshlrev_b32_e32 v62, 2, v8
	v_lshlrev_b32_e32 v64, 2, v6
	v_lshlrev_b32_e32 v66, 2, v4
	s_branch .LBB0_1218

;     __device__ __forceinline__ bool idx(int i, int& Lp, int& half) const {
;         const int R = n / G, T = n % G; long L; half = 0;
;         if (i == R && T > 0 && 2 * T <= G) { if (c >= 2 * T) return false; L = (long)R * G + (c >> 1); half = 1 + (c & 1); }
;         else { L = (long)i * G + c; if (L >= n) return false; }
;         const int w = (int)L, q = n / 8, r = n % 8, xcd = w % 8, off = w / 8;
;         Lp = (xcd < r ? xcd * (q + 1) : r * (q + 1) + (xcd - r) * q) + off; return true;
; __global__ void __launch_bounds__(512, 2) hybrid_fwd(Params p_unused) {
;     ...
;         if (PHM & 4096) { const Params p = ldp(); SchedFfn1 S{{nM * 22, G, c}, p.ws, (size_t)0 * WSET}; g8::EpiSwiglu E; g8::gemm_phase(wv, lds, 1024, S, E); }
.Lgb_done_7:
.LBB0_1288:
	s_or_b64 exec, exec, s[6:7]
	s_mov_b32 s101, 0
	s_mov_b64 s[0:1], s[90:91]
	s_waitcnt lgkmcnt(0)
	s_barrier
	s_load_dwordx2 s[18:19], s[0:1], 0xa8
	s_mul_i32 s56, s28, 22
	v_readlane_b32 s1, v254, 1
	s_mul_hi_u32 s1, s56, s1
	v_readlane_b32 s6, v254, 4
	s_mul_i32 s3, s1, s6
	s_sub_i32 s3, s56, s3
	s_add_i32 s4, s1, 1
	s_sub_i32 s5, s3, s6
	s_cmp_ge_u32 s3, s6
	s_cselect_b32 s1, s4, s1
	s_cselect_b32 s3, s5, s3
	s_add_i32 s4, s1, 1
	s_cmp_ge_u32 s3, s6
	s_cselect_b32 s1, s4, s1
	s_xor_b32 s1, s1, s45
	s_sub_i32 s1, s1, s45
	s_mul_i32 s3, s1, s44
	s_sub_i32 s8, s56, s3
	s_cmp_lg_u32 s1, 0
	v_mbcnt_lo_u32_b32 v0, -1, 0
	v_mbcnt_hi_u32_b32 v0, -1, v0
	s_cselect_b64 s[6:7], -1, 0
	v_add_u32_e32 v2, s89, v0
	s_and_b64 vcc, exec, s[6:7]
	v_readfirstlane_b32 s0, v2
	s_cbranch_vccnz .LBB0_1292
	s_lshl_b32 s3, s8, 1
	s_cmp_le_i32 s3, s44
	s_cbranch_scc0 .LBB0_1291
	s_cmp_lt_i32 s96, s3
	s_mov_b64 s[6:7], 0
	s_cselect_b64 s[4:5], -1, 0
	s_branch .LBB0_1293

;     __device__ __forceinline__ bool next(int i, Unit& u) const {
;         u.ldo = 1024; u.cmax = flags;
;         const int r0 = (256 + G - 1) / G;
;         if (i < r0) { g8::ListOrder L{256, G, c}; int q; if (!L.idx(i, q)) return false;
;             const int pm = q >> 2, pn = q & 3; const size_t ro = (size_t)pm * 256 * 1024 + pn * 256;
;             u.a = A + (size_t)pm * a_tile_bytes; u.b = Bt + (size_t)pn * b_tile_bytes;
;             u.p1 = (flags & 1) ? (const float*)((const bf16_t*)base_lat + ro) : (const float*)base_lat + ro;
;             u.o = (flags & 2) ? (char*)((bf16_t*)out_lat + ro) : (char*)((float*)out_lat + ro);
;             u.p2 = gate + (size_t)(pm >> 3) * 6144 + pn * 256; u.nt = ntk; u.mode = 0; u.half = 0; u.mk = -1; u.mneg = 0; return true; }
;         if (!with_ctx) return false;
;         g8::ListOrder L{32 * nsp, G, c}; int q; if (!L.idx(i - r0, q)) return false;
;         const int un = q / nsp, part = q % nsp, pm = un >> 2, pn = un & 3, k0 = part * ntp; const size_t ro = (size_t)pm * 256 * 1024 + pn * 256;
;         u.a = A + (size_t)(64 + pm) * a_tile_bytes + (size_t)k0 * 128; u.b = Bt + (size_t)pn * b_tile_bytes + (size_t)k0 * 128;
;         u.p1 = nullptr; u.o = (char*)(ws + OFF_S) + ((size_t)part * 2048 * 1024 + ro) * 2; u.p2 = gate + (size_t)8 * 6144 + pn * 256;
;         u.nt = (part == nsp - 1) ? (ntk - k0) : ntp; u.mode = 1; u.half = 0; u.mk = -1; u.mneg = 0; return true;
; __global__ void __launch_bounds__(512, 2) hybrid_fwd(Params p_unused) {
;     ...
;         if (PHM & 8192) { const Params p = ldp(); const float* mod = (const float*)(p.ws + OFF_MOD); SchedRes S{G, c, need_ctx ? 1 : 0, 5, 44, 8, p.ws, (const char*)(p.ws + OFF_U), (size_t)256 * DFF * 2, (const char*)(p.ws + OFF_W2 + (size_t)0 * WSET), (size_t)256 * DFF * 2,
;                      (const void*)(p.ws + OFF_XB), l == 0 ? (void*)(p.ws + OFF_XB) : (void*)p.out, l == 0 ? 3 : 1, mod + (size_t)l * 9 * 6144 + 5120};
;           g8::EpiRes E; g8::gemm_phase(wv, lds, DFF, S, E); }
.Lgb_done_8:
.LBB0_1405:
	s_or_b64 exec, exec, s[6:7]
	s_mov_b64 s[0:1], s[90:91]
	s_waitcnt lgkmcnt(0)
	s_barrier
	s_load_dwordx4 s[16:19], s[0:1], 0xa0
	v_readlane_b32 s6, v254, 5
	v_mbcnt_lo_u32_b32 v0, -1, 0
	v_mbcnt_hi_u32_b32 v0, -1, v0
	v_readlane_b32 s7, v254, 6
	v_add_u32_e32 v2, s89, v0
	s_waitcnt lgkmcnt(0)
	s_add_u32 s0, s18, 0x2c00000
	s_addc_u32 s1, s19, 0
	s_add_u32 s46, s18, 0xc04c000
	s_addc_u32 s47, s19, 0
	s_add_u32 s48, s18, 0xc60c000
	s_addc_u32 s49, s19, 0
	s_and_b64 s[4:5], s[86:87], exec
	s_cselect_b32 s50, s49, s17
	s_cselect_b32 s51, s48, s16
	s_add_u32 s4, s18, s20
	s_addc_u32 s5, s19, s21
	s_add_u32 s52, s4, 0xfa51000
	s_addc_u32 s53, s5, 0
	v_readfirstlane_b32 s56, v2
	s_mov_b64 s[16:17], -1
	s_and_b64 vcc, exec, s[6:7]
	s_cbranch_vccz .LBB0_1410
	s_mov_b64 s[16:17], 0
	s_and_b64 vcc, exec, s[10:11]
	s_mov_b64 s[14:15], 0
	s_cbranch_vccnz .LBB0_1409
	v_readlane_b32 s6, v254, 50
	v_readlane_b32 s7, v254, 51
	s_andn2_b64 vcc, exec, s[6:7]
	s_cbranch_vccnz .LBB0_1409
	v_readlane_b32 s3, v254, 53
	s_add_u32 s3, s0, s3
	v_readlane_b32 s6, v254, 52
	s_addc_u32 s6, s1, s6
	v_readlane_b32 s8, v254, 20
	v_readlane_b32 s9, v254, 21
	s_add_u32 s26, s3, s8
	s_addc_u32 s27, s6, s9
	v_readlane_b32 s3, v254, 54
	s_add_u32 s3, s46, s3
	s_addc_u32 s6, s47, 0
	s_add_u32 s28, s3, s8
	s_addc_u32 s29, s6, s9
	v_readlane_b32 s6, v254, 25
	v_readlane_b32 s7, v254, 26
	s_add_u32 s3, s18, s6
	s_addc_u32 s6, s19, s7
	v_readlane_b32 s8, v254, 22
	v_readlane_b32 s9, v254, 23
	s_add_u32 s3, s3, s8
	s_addc_u32 s6, s6, s9
	v_readlane_b32 s7, v254, 24
	s_add_u32 s3, s3, s7
	s_addc_u32 s6, s6, 0
	s_add_u32 s8, s3, 0x9920000
	s_addc_u32 s9, s6, 0
	v_readlane_b32 s3, v254, 58
	s_add_u32 s3, s4, s3
	s_addc_u32 s6, s5, 0
	s_add_u32 s24, s3, 0xfa81000
	s_addc_u32 s25, s6, 0
	s_mov_b64 s[6:7], 0
	s_mov_b32 s86, 1
	s_mov_b64 s[14:15], -1

; #define GRID_SYNC() do { const Params pb = ldp(); grid_bar(wv, (unsigned*)(pb.ws + OFF_BAR), (volatile LAS unsigned*)(lds + QWORD_OFF + 4)); } while (0)
; __global__ void __launch_bounds__(512, 2) hybrid_fwd(Params p_unused) {
;     ...
;         if (l == 0) GRID_SYNC();
;     }
.Lgb_done_9:
	s_getpc_b64 s[98:99]
